# layer 1: no grid barrier between merge of half-batch 0 and in-projection of half-batch 1 (disjoint data)
# speedup vs baseline: 1.0059x; 1.0005x over previous
; __global__ void __launch_bounds__(NTHREADS, 2) fwd_megakernel(Args A) {
;     ...
;             for (int hb = 0; hb < 2; ++hb) {
;                 const int row_base = hb * 8192;
;                 {
;                     pg8::Gemm g{XB + (size_t)row_base * DM, WIN, 8192, 10240, 1024}; pg8::StaticOrder S; S.init(8192, 10240, G, bx);
;                     EpiIn<1> E{ssq + 1 * MROWS, row_base, PROJ, nullptr, nullptr, nullptr, Y, nullptr, 0, nullptr, nullptr};
;                     pg8::gemm_phase<EpiIn<1>, pg8::StaticOrder, true, true>(lds, g, S, E);
.Lskip_gs1:
	v_readlane_b32 s28, v255, 28
	v_readlane_b32 s29, v255, 29
	s_mov_b32 s1, 1
	s_mov_b64 s[6:7], 0
	s_branch .LBB0_117

; #define GSYNC() xcd_barrier(xbar)
; __global__ void __launch_bounds__(NTHREADS, 2) fwd_megakernel(Args A) {
;     ...
;                     *(v4u*)(Y + (size_t)row_base * DM + off) = o;
;                 }
;                 GSYNC();
.LBB0_404:
	s_or_b64 exec, exec, s[0:1]
	v_readlane_b32 s2, v255, 35
	v_readlane_b32 s3, v255, 36
	s_nop 1
	s_cmp_eq_u64 s[2:3], 0
	s_cbranch_scc1 .Lskip_gs1
	s_waitcnt vmcnt(0)
	s_barrier
	s_and_saveexec_b64 s[0:1], s[86:87]
	v_readlane_b32 s28, v255, 28
	v_readlane_b32 s29, v255, 29
	s_cbranch_execz .LBB0_116
	v_readlane_b32 s2, v254, 55
	s_waitcnt vmcnt(0) expcnt(0) lgkmcnt(0)
	s_nop 0
	v_mov_b32_e32 v1, s2
	ds_read_b32 v3, v1
	v_readlane_b32 s2, v254, 56
	s_waitcnt lgkmcnt(0)
	v_cmp_ne_u32_e32 vcc, 0, v3
	v_mov_b32_e32 v1, s2
	ds_read_b32 v2, v1
	s_cbranch_vccnz .LBB0_420
	s_mov_b32 s8, 1
	s_branch .LBB0_408
